# attention key loop: next-tile K/V addresses from bases pre-biased once per unit (2 instead of 14 address instructions per iteration at the loop head), on top of the per-half loop copies
# baseline (speedup 1.0000x reference)
.Lan_entry:
	v_cvt_f32_i32_e32 v255, v231
	v_add_f32_e32 v255, 0x42800000, v255
	v_cmp_eq_u32_e32 vcc, 0, v203
	s_nop 1
	v_cndmask_b32_e32 v208, v229, v255, vcc
	v_add_f32_e32 v255, 0x80000000, v208
	v_fma_f32 v96, -v201, |v255|, v253
	v_add_f32_e32 v255, 0xbf800000, v208
	v_fma_f32 v97, -v201, |v255|, v253
	v_add_f32_e32 v255, 0xc0000000, v208
	v_fma_f32 v98, -v201, |v255|, v253
	v_add_f32_e32 v255, 0xc0400000, v208
	v_fma_f32 v99, -v201, |v255|, v253
	v_add_f32_e32 v255, 0xc0800000, v208
	v_fma_f32 v100, -v201, |v255|, v253
	v_add_f32_e32 v255, 0xc0a00000, v208
	v_fma_f32 v101, -v201, |v255|, v253
	v_add_f32_e32 v255, 0xc0c00000, v208
	v_fma_f32 v102, -v201, |v255|, v253
	v_add_f32_e32 v255, 0xc0e00000, v208
	v_fma_f32 v103, -v201, |v255|, v253
	v_add_f32_e32 v255, 0xc1800000, v208
	v_fma_f32 v104, -v201, |v255|, v253
	v_add_f32_e32 v255, 0xc1880000, v208
	v_fma_f32 v105, -v201, |v255|, v253
	v_add_f32_e32 v255, 0xc1900000, v208
	v_fma_f32 v106, -v201, |v255|, v253
	v_add_f32_e32 v255, 0xc1980000, v208
	v_fma_f32 v107, -v201, |v255|, v253
	v_add_f32_e32 v255, 0xc1a00000, v208
	v_fma_f32 v108, -v201, |v255|, v253
	v_add_f32_e32 v255, 0xc1a80000, v208
	v_fma_f32 v109, -v201, |v255|, v253
	v_add_f32_e32 v255, 0xc1b00000, v208
	v_fma_f32 v110, -v201, |v255|, v253
	v_add_f32_e32 v255, 0xc1b80000, v208
	v_fma_f32 v111, -v201, |v255|, v253
	v_mov_b32_e32 v80, 0xff61b1e6
	v_mov_b32_e32 v81, 0xff61b1e6
	v_mov_b32_e32 v82, 0xff61b1e6
	v_mov_b32_e32 v83, 0xff61b1e6
	v_mov_b32_e32 v84, 0xff61b1e6
	v_mov_b32_e32 v85, 0xff61b1e6
	v_mov_b32_e32 v86, 0xff61b1e6
	v_mov_b32_e32 v87, 0xff61b1e6
	v_mov_b32_e32 v88, 0xff61b1e6
	v_mov_b32_e32 v89, 0xff61b1e6
	v_mov_b32_e32 v90, 0xff61b1e6
	v_mov_b32_e32 v91, 0xff61b1e6
	v_mov_b32_e32 v92, 0xff61b1e6
	v_mov_b32_e32 v93, 0xff61b1e6
	v_mov_b32_e32 v94, 0xff61b1e6
	v_mov_b32_e32 v95, 0xff61b1e6
	s_add_u32 s94, s62, 0x8f61000
	s_addc_u32 s95, s63, 0
	s_add_u32 s96, s62, 0x18803000
	s_addc_u32 s97, s63, 0
	v_lshl_add_u64 v[206:207], v[206:207], 0, s[94:95]
	v_lshl_add_u64 v[204:205], v[204:205], 0, s[96:97]
	s_mov_b32 s94, 0x28000
	s_mov_b32 s95, 0
	s_mov_b32 s96, 0x402000
	s_mov_b32 s97, 0
	s_cmp_eq_u32 s85, 1
	s_cbranch_scc1 .Lan_327_h1
.Lan_327_h0:
	s_and_b32 s88, s90, 1
	s_mul_i32 s33, s88, 0x4400
	v_add_u32_e32 v235, s33, v230
	s_add_i32 s87, s90, 1
	s_and_b32 s89, s87, 1
	s_mul_i32 s33, s89, 0x4800
	v_add_u32_e32 v234, s33, v215
	ds_read_b128 v[64:67], v235
	ds_read_b128 v[68:71], v235 offset:32
	ds_read_b128 v[72:75], v235 offset:64
	ds_read_b128 v[76:79], v235 offset:96
	ds_read_b128 v[160:163], v234 offset:34816
	s_cmp_lt_i32 s87, s38
	s_cselect_b64 s[54:55], -1, 0
	s_cmp_ge_i32 s87, s38
	s_cbranch_scc1 .Lan_329_h0
	v_lshl_add_u64 v[244:245], v[206:207], 0, s[94:95]
	global_load_dwordx4 v[128:131], v[206:207], off
	global_load_dwordx4 v[132:135], v[244:245], off
.Lan_329_h0:
	s_cmp_lt_i32 s90, s38
	s_cselect_b64 s[56:57], -1, 0
	s_cmp_ge_i32 s90, s38
	s_cbranch_scc1 .Lan_331_h0
	v_lshl_add_u64 v[246:247], v[204:205], 0, s[96:97]
	global_load_dwordx4 v[136:139], v[204:205], off offset:3968
	global_load_dwordx4 v[140:143], v[246:247], off offset:3968
